# out-proj GEMM DMA loads also in scalar-base form; accumulators cleared with 64 v_mov_b64 instead of 128 v_mov_b32 per tile (both GEMMs)
# speedup vs baseline: 1.0091x; 1.0012x over previous
; #define PG8_STAGE(bufoff, gbase, voff) do { _Pragma("unroll") for (int _i = 0; _i < 2; ++_i) \
;         __builtin_amdgcn_global_load_lds((const unsigned*)((const char*)(gbase) + (voff)[_i]), (LAS unsigned*)(lds + (bufoff) + ldsw + _i * 8192), 16, 0, 0); } while (0)
; #define PG8_WAIT_V(n) asm volatile("s_waitcnt vmcnt(" #n ")" ::: "memory")
; #define PG8_BAR __builtin_amdgcn_s_barrier()
; template <class Epi>
; DI void gemm_phase(LAS unsigned char* lds, const Gemm g, const StaticOrder& S, const Epi& E, const int tid) {
;     ...
;     Unit cur, nxt; int ui = 0;
;     if (!S.next(0, cur)) return;
;     f32x4 acc[2][2][4][2];
; #pragma unroll
;     for (int a = 0; a < 2; ++a)
; #pragma unroll
;         for (int b = 0; b < 2; ++b)
; #pragma unroll
;             for (int m = 0; m < 4; ++m)
; #pragma unroll
;                 for (int n = 0; n < 2; ++n) acc[a][b][m][n] = (f32x4){0.f, 0.f, 0.f, 0.f};
;     bf16x8 At[4][2], B0[2][2], B1[2][2];
;     const char* cA = (const char*)g.A + (size_t)cur.pm * tstepA; const char* cB = (const char*)g.Bt + (size_t)cur.pn * tstepB;
;     PG8_STAGE(PG8_SB(0, 0), cB, voffB); PG8_STAGE(PG8_SA(0, 0), cA, voffA); PG8_STAGE(PG8_SB(0, 1), cB + hstepB, voffB); PG8_STAGE(PG8_SA(0, 1), cA + hstepA, voffA);
;     if (wr == 1) PG8_BAR;
;     PG8_WAIT_V(4); PG8_BAR;
;     PG8_STAGE(PG8_SB(1, 0), cB + kstep, voffB); PG8_STAGE(PG8_SA(1, 0), cA + PG8_KTA(1), voffA); PG8_STAGE(PG8_SB(1, 1), cB + hstepB + kstep, voffB);
;     PG8_WAIT_V(6); PG8_BAR;
;     for (;;) {
;         const bool has_next = S.next(ui + 1, nxt);
;         const char* nA = has_next ? (const char*)g.A + (size_t)nxt.pm * tstepA : cA; const char* nB = has_next ? (const char*)g.Bt + (size_t)nxt.pn * tstepB : cB;
.LBB0_61:
	s_ashr_i32 s43, s42, 31
	v_cmp_lt_i64_e32 vcc, s[6:7], v[142:143]
	s_lshl_b64 s[6:7], s[42:43], 20
	s_add_u32 s46, s70, s6
	s_addc_u32 s47, s71, s7
	s_and_b64 s[6:7], vcc, exec
	s_cselect_b32 s30, s47, s45
	s_cselect_b32 s31, s46, s44
	s_ashr_i32 s39, s38, 31
	s_lshl_b64 s[6:7], s[38:39], 20
	s_add_u32 s48, s36, s6
	s_addc_u32 s49, s37, s7
	s_and_b64 s[6:7], vcc, exec
	s_cselect_b32 s39, s49, s5
	s_cselect_b32 s43, s48, s4
	s_add_u32 s64, s31, 0x80
	s_addc_u32 s65, s30, 0
	s_add_u32 s6, s44, 0x80080
	s_addc_u32 s7, s45, 0
	s_add_u32 s66, s4, 0x100
	v_mov_b64_e32 v[2:3], 0
	s_addc_u32 s67, s5, 0
	s_mov_b32 s68, -2
	s_mov_b64 s[4:5], 0
	v_mov_b64_e32 v[4:5], 0
	v_mov_b64_e32 v[6:7], 0
	v_mov_b64_e32 v[8:9], 0
	v_mov_b64_e32 v[10:11], 0
	v_mov_b64_e32 v[12:13], 0
	v_mov_b64_e32 v[14:15], 0
	v_mov_b64_e32 v[16:17], 0
	v_mov_b64_e32 v[18:19], 0
	v_mov_b64_e32 v[20:21], 0
	v_mov_b64_e32 v[22:23], 0
	v_mov_b64_e32 v[24:25], 0
	v_mov_b64_e32 v[26:27], 0
	v_mov_b64_e32 v[28:29], 0
	v_mov_b64_e32 v[30:31], 0
	v_mov_b64_e32 v[32:33], 0
	v_mov_b64_e32 v[34:35], 0
	v_mov_b64_e32 v[36:37], 0
	v_mov_b64_e32 v[38:39], 0
	v_mov_b64_e32 v[40:41], 0
	v_mov_b64_e32 v[42:43], 0
	v_mov_b64_e32 v[44:45], 0
	v_mov_b64_e32 v[46:47], 0
	v_mov_b64_e32 v[48:49], 0
	v_mov_b64_e32 v[50:51], 0
	v_mov_b64_e32 v[52:53], 0
	v_mov_b64_e32 v[54:55], 0
	v_mov_b64_e32 v[56:57], 0
	v_mov_b64_e32 v[58:59], 0
	v_mov_b64_e32 v[60:61], 0
	v_mov_b64_e32 v[62:63], 0
	v_mov_b64_e32 v[64:65], 0
	v_mov_b64_e32 v[66:67], 0
	v_mov_b64_e32 v[68:69], 0
	v_mov_b64_e32 v[70:71], 0
	v_mov_b64_e32 v[72:73], 0
	v_mov_b64_e32 v[74:75], 0
	v_mov_b64_e32 v[76:77], 0
	v_mov_b64_e32 v[78:79], 0
	v_mov_b64_e32 v[80:81], 0
	v_mov_b64_e32 v[82:83], 0
	v_mov_b64_e32 v[84:85], 0
	v_mov_b64_e32 v[86:87], 0
	v_mov_b64_e32 v[88:89], 0
	v_mov_b64_e32 v[90:91], 0
	v_mov_b64_e32 v[92:93], 0
	v_mov_b64_e32 v[94:95], 0
	v_mov_b64_e32 v[96:97], 0
	v_mov_b64_e32 v[98:99], 0
	v_mov_b64_e32 v[100:101], 0
	v_mov_b64_e32 v[102:103], 0
	v_mov_b64_e32 v[104:105], 0
	v_mov_b64_e32 v[106:107], 0
	v_mov_b64_e32 v[108:109], 0
	v_mov_b64_e32 v[110:111], 0
	v_mov_b64_e32 v[112:113], 0
	v_mov_b64_e32 v[114:115], 0
	v_mov_b64_e32 v[116:117], 0
	v_mov_b64_e32 v[118:119], 0
	v_mov_b64_e32 v[120:121], 0
	v_mov_b64_e32 v[122:123], 0
	v_mov_b64_e32 v[124:125], 0
	v_mov_b64_e32 v[126:127], 0
	v_mov_b64_e32 v[128:129], 0
	v_lshl_add_u64 v[144:145], s[6:7], 0, v[138:139]
	v_lshl_add_u64 v[146:147], s[6:7], 0, v[140:141]
	s_add_u32 s6, s44, s4
	s_addc_u32 s7, s45, s5
	s_add_u32 s8, s6, 0x100
	s_addc_u32 s9, s7, 0
	s_add_u32 s69, s66, s4
	s_addc_u32 s78, s67, s5
	s_add_u32 s86, s6, 0x180
	s_addc_u32 s87, s7, 0
	s_cmpk_eq_i32 s4, 0xf00
	s_cselect_b32 s51, s30, s9
	s_cselect_b32 s50, s31, s8
	s_cselect_b32 s7, s39, s78
	s_cselect_b32 s6, s43, s69
	s_cselect_b32 s9, s65, s87
	s_cselect_b32 s8, s64, s86
	s_add_u32 s86, s44, s4
	s_addc_u32 s87, s45, s5
	s_add_u32 s86, s86, 0x80080
	s_addc_u32 s87, s87, 0

; #define PG8_STAGE(bufoff, gbase, voff) do { _Pragma("unroll") for (int _i = 0; _i < 2; ++_i) \
;         __builtin_amdgcn_global_load_lds((const unsigned*)((const char*)(gbase) + (voff)[_i]), (LAS unsigned*)(lds + (bufoff) + ldsw + _i * 8192), 16, 0, 0); } while (0)
; template <class Epi>
; DI void gemm_phase(LAS unsigned char* lds, const Gemm g, const StaticOrder& S, const Epi& E, const int tid) {
;     ...
;     Unit cur, nxt; int ui = 0;
;     if (!S.next(0, cur)) return;
;     f32x4 acc[2][2][4][2];
; #pragma unroll
;     for (int a = 0; a < 2; ++a)
; #pragma unroll
;         for (int b = 0; b < 2; ++b)
; #pragma unroll
;             for (int m = 0; m < 4; ++m)
; #pragma unroll
;                 for (int n = 0; n < 2; ++n) acc[a][b][m][n] = (f32x4){0.f, 0.f, 0.f, 0.f};
;     bf16x8 At[4][2], B0[2][2], B1[2][2];
;     const char* cA = (const char*)g.A + (size_t)cur.pm * tstepA; const char* cB = (const char*)g.Bt + (size_t)cur.pn * tstepB;
;     PG8_STAGE(PG8_SB(0, 0), cB, voffB); PG8_STAGE(PG8_SA(0, 0), cA, voffA); PG8_STAGE(PG8_SB(0, 1), cB + hstepB, voffB); PG8_STAGE(PG8_SA(0, 1), cA + hstepA, voffA);
;     if (wr == 1) PG8_BAR;
;     PG8_WAIT_V(4); PG8_BAR;
;     PG8_STAGE(PG8_SB(1, 0), cB + kstep, voffB); PG8_STAGE(PG8_SA(1, 0), cA + PG8_KTA(1), voffA); PG8_STAGE(PG8_SB(1, 1), cB + hstepB + kstep, voffB);
;     PG8_WAIT_V(6); PG8_BAR;
;     for (;;) {
;         const bool has_next = S.next(ui + 1, nxt);
;         const char* nA = has_next ? (const char*)g.A + (size_t)nxt.pm * tstepA : cA; const char* nB = has_next ? (const char*)g.Bt + (size_t)nxt.pn * tstepB : cB;
;         for (int t = 0; t < nt; t += 2) {
;             const bool last = (t == nt - 2);
;             const char* a1 = cA + PG8_KTA(t + 1);
;             const char* a2 = last ? nA : cA + PG8_KTA(t + 2); const char* b2 = last ? nB : cB + (size_t)(t + 2) * kstep;
;             const char* a3 = last ? nA + PG8_KTA(1) : cA + PG8_KTA(t + 3); const char* b3 = b2 + kstep;
;             PG8_LDB(B0, 0, 0); PG8_SCHED; PG8_LDA(At, 0, 0); PG8_STAGE(PG8_SA(1, 1), a1 + hstepA, voffA);
;             PG8_WAIT_L(8); PG8_BAR; PG8_WAIT_L(0); PG8_MMA(0, 0, At, B0); PG8_BAR; PG8_SCHED;
;             PG8_LDB(B1, 0, 1); PG8_STAGE(PG8_SB(0, 0), b2, voffB);
;             PG8_BAR; PG8_WAIT_L(0); PG8_MMA(0, 1, At, B1); PG8_BAR;
;             PG8_LDA(At, 0, 1); PG8_STAGE(PG8_SA(0, 0), a2, voffA);
.LBB0_285:
	s_ashr_i32 s41, s40, 31
	s_lshl_b64 s[6:7], s[40:41], 20
	s_add_u32 s44, s34, s6
	s_addc_u32 s45, s35, s7
	s_and_b64 s[6:7], s[38:39], exec
	s_cselect_b32 s30, s45, s5
	s_cselect_b32 s31, s44, s4
	s_add_u32 s38, s4, 0x100
	v_mov_b64_e32 v[2:3], 0
	s_addc_u32 s39, s5, 0
	s_movk_i32 s41, 0x3000
	s_mov_b32 s56, 0x18000
	s_mov_b32 s57, -2
	v_mov_b64_e32 v[4:5], 0
	v_mov_b64_e32 v[6:7], 0
	v_mov_b64_e32 v[8:9], 0
	v_mov_b64_e32 v[10:11], 0
	v_mov_b64_e32 v[12:13], 0
	v_mov_b64_e32 v[14:15], 0
	v_mov_b64_e32 v[16:17], 0
	v_mov_b64_e32 v[18:19], 0
	v_mov_b64_e32 v[20:21], 0
	v_mov_b64_e32 v[22:23], 0
	v_mov_b64_e32 v[24:25], 0
	v_mov_b64_e32 v[26:27], 0
	v_mov_b64_e32 v[28:29], 0
	v_mov_b64_e32 v[30:31], 0
	v_mov_b64_e32 v[32:33], 0
	v_mov_b64_e32 v[34:35], 0
	v_mov_b64_e32 v[36:37], 0
	v_mov_b64_e32 v[38:39], 0
	v_mov_b64_e32 v[40:41], 0
	v_mov_b64_e32 v[42:43], 0
	v_mov_b64_e32 v[44:45], 0
	v_mov_b64_e32 v[46:47], 0
	v_mov_b64_e32 v[48:49], 0
	v_mov_b64_e32 v[50:51], 0
	v_mov_b64_e32 v[52:53], 0
	v_mov_b64_e32 v[54:55], 0
	v_mov_b64_e32 v[56:57], 0
	v_mov_b64_e32 v[58:59], 0
	v_mov_b64_e32 v[60:61], 0
	v_mov_b64_e32 v[62:63], 0
	v_mov_b64_e32 v[64:65], 0
	v_mov_b64_e32 v[66:67], 0
	v_mov_b64_e32 v[68:69], 0
	v_mov_b64_e32 v[70:71], 0
	v_mov_b64_e32 v[72:73], 0
	v_mov_b64_e32 v[74:75], 0
	v_mov_b64_e32 v[76:77], 0
	v_mov_b64_e32 v[78:79], 0
	v_mov_b64_e32 v[80:81], 0
	v_mov_b64_e32 v[82:83], 0
	v_mov_b64_e32 v[84:85], 0
	v_mov_b64_e32 v[86:87], 0
	v_mov_b64_e32 v[88:89], 0
	v_mov_b64_e32 v[90:91], 0
	v_mov_b64_e32 v[92:93], 0
	v_mov_b64_e32 v[94:95], 0
	v_mov_b64_e32 v[96:97], 0
	v_mov_b64_e32 v[98:99], 0
	v_mov_b64_e32 v[100:101], 0
	v_mov_b64_e32 v[102:103], 0
	v_mov_b64_e32 v[104:105], 0
	v_mov_b64_e32 v[106:107], 0
	v_mov_b64_e32 v[108:109], 0
	v_mov_b64_e32 v[110:111], 0
	v_mov_b64_e32 v[112:113], 0
	v_mov_b64_e32 v[114:115], 0
	v_mov_b64_e32 v[116:117], 0
	v_mov_b64_e32 v[118:119], 0
	v_mov_b64_e32 v[120:121], 0
	v_mov_b64_e32 v[122:123], 0
	v_mov_b64_e32 v[124:125], 0
	v_mov_b64_e32 v[126:127], 0
	v_mov_b64_e32 v[128:129], 0
	s_branch .LBB0_287
.LBB0_286:
	s_add_i32 s8, s56, 0xfffe8000
	s_add_i32 s9, s41, 0xffffd000
	s_and_b32 s8, s8, 0xe0000
	s_and_b32 s9, s9, 0x2000
	s_or_b32 s58, s9, s8
	s_add_i32 s8, s56, 0xffff8000
	s_add_i32 s9, s41, 0xfffff000
	s_and_b32 s8, s8, 0x1e0000
	s_and_b32 s9, s9, 0x2000
	s_or_b32 s8, s8, s9
	s_add_u32 s8, s0, s8
	s_addc_u32 s9, s1, 0
	s_and_b64 s[6:7], exec, s[6:7]
	s_cselect_b32 s9, s43, s9
	s_cselect_b32 s8, s42, s8
	s_cselect_b32 s7, s30, s39
	s_cselect_b32 s6, s31, s38
	s_add_i32 s60, 0, 0x10000
	v_add_u32_e32 v158, s60, v139
	ds_read_b128 v[142:145], v158
	ds_read_b128 v[146:149], v158 offset:1024
	ds_read_b128 v[150:153], v158 offset:2048
	ds_read_b128 v[158:161], v158 offset:3072
	s_add_u32 s58, s0, s58
	s_addc_u32 s59, s1, 0
	s_add_u32 s58, s58, 0x10800
	s_addc_u32 s59, s59, 0
	s_add_i32 m0, s29, 0xc000
	ds_read_b128 v[162:165], v141
	ds_read_b128 v[166:169], v141 offset:1024
	ds_read_b128 v[178:181], v141 offset:2048
	ds_read_b128 v[182:185], v141 offset:3072
	ds_read_b128 v[186:189], v141 offset:4096
	ds_read_b128 v[190:193], v141 offset:5120
	ds_read_b128 v[194:197], v141 offset:6144
	ds_read_b128 v[198:201], v141 offset:7168
	global_load_lds_dwordx4 v130, s[58:59]
	s_add_i32 m0, s29, 0xe000
	s_nop 0
	global_load_lds_dwordx4 v132, s[58:59]
	s_waitcnt lgkmcnt(8)
	s_barrier
	s_waitcnt lgkmcnt(0)
	s_setprio 1
	s_waitcnt lgkmcnt(0)
	v_mfma_f32_16x16x32_bf16 v[126:129], v[142:145], v[162:165], v[126:129]
	v_mfma_f32_16x16x32_bf16 v[122:125], v[150:153], v[162:165], v[122:125]
	v_mfma_f32_16x16x32_bf16 v[118:121], v[142:145], v[178:181], v[118:121]
	v_mfma_f32_16x16x32_bf16 v[114:117], v[150:153], v[178:181], v[114:117]
	v_mfma_f32_16x16x32_bf16 v[102:105], v[142:145], v[186:189], v[102:105]
	v_mfma_f32_16x16x32_bf16 v[98:101], v[150:153], v[186:189], v[98:101]
	v_mfma_f32_16x16x32_bf16 v[86:89], v[142:145], v[194:197], v[86:89]
	v_mfma_f32_16x16x32_bf16 v[82:85], v[150:153], v[194:197], v[82:85]
	v_mfma_f32_16x16x32_bf16 v[126:129], v[146:149], v[166:169], v[126:129]
	v_mfma_f32_16x16x32_bf16 v[122:125], v[158:161], v[166:169], v[122:125]
	v_mfma_f32_16x16x32_bf16 v[118:121], v[146:149], v[182:185], v[118:121]
	v_mfma_f32_16x16x32_bf16 v[114:117], v[158:161], v[182:185], v[114:117]
	v_mfma_f32_16x16x32_bf16 v[102:105], v[146:149], v[190:193], v[102:105]
	v_mfma_f32_16x16x32_bf16 v[98:101], v[158:161], v[190:193], v[98:101]
	v_mfma_f32_16x16x32_bf16 v[86:89], v[146:149], v[198:201], v[86:89]
	v_mfma_f32_16x16x32_bf16 v[82:85], v[158:161], v[198:201], v[82:85]
	s_setprio 0
	s_barrier
	s_add_i32 s61, 0, 0x14000
	v_add_u32_e32 v170, s61, v139
	s_add_i32 s58, s60, s28
	ds_read_b128 v[202:205], v170
	ds_read_b128 v[206:209], v170 offset:1024
	ds_read_b128 v[210:213], v170 offset:2048
	ds_read_b128 v[214:217], v170 offset:3072
	s_mov_b32 m0, s58
	s_nop 0
	global_load_lds_dwordx4 v0, s[6:7]
	s_add_i32 m0, s58, 0x2000
	s_nop 0
	global_load_lds_dwordx4 v134, s[6:7]
	s_barrier
	s_waitcnt lgkmcnt(0)
	s_setprio 1
	s_waitcnt lgkmcnt(0)
	v_mfma_f32_16x16x32_bf16 v[110:113], v[202:205], v[162:165], v[110:113]
	v_mfma_f32_16x16x32_bf16 v[106:109], v[210:213], v[162:165], v[106:109]
	v_mfma_f32_16x16x32_bf16 v[94:97], v[202:205], v[178:181], v[94:97]
	v_mfma_f32_16x16x32_bf16 v[90:93], v[210:213], v[178:181], v[90:93]
	v_mfma_f32_16x16x32_bf16 v[78:81], v[202:205], v[186:189], v[78:81]
	v_mfma_f32_16x16x32_bf16 v[74:77], v[210:213], v[186:189], v[74:77]
	v_mfma_f32_16x16x32_bf16 v[70:73], v[202:205], v[194:197], v[70:73]
	v_mfma_f32_16x16x32_bf16 v[66:69], v[210:213], v[194:197], v[66:69]
	v_mfma_f32_16x16x32_bf16 v[110:113], v[206:209], v[166:169], v[110:113]
	v_mfma_f32_16x16x32_bf16 v[106:109], v[214:217], v[166:169], v[106:109]
	v_mfma_f32_16x16x32_bf16 v[94:97], v[206:209], v[182:185], v[94:97]
	v_mfma_f32_16x16x32_bf16 v[90:93], v[214:217], v[182:185], v[90:93]
	v_mfma_f32_16x16x32_bf16 v[78:81], v[206:209], v[190:193], v[78:81]
	v_mfma_f32_16x16x32_bf16 v[74:77], v[214:217], v[190:193], v[74:77]
	v_mfma_f32_16x16x32_bf16 v[70:73], v[206:209], v[198:201], v[70:73]
	v_mfma_f32_16x16x32_bf16 v[66:69], v[214:217], v[198:201], v[66:69]
	s_setprio 0
	s_mov_b32 m0, s29
	s_barrier
; #define PG8_STAGE(bufoff, gbase, voff) do { _Pragma("unroll") for (int _i = 0; _i < 2; ++_i) \
;         __builtin_amdgcn_global_load_lds((const unsigned*)((const char*)(gbase) + (voff)[_i]), (LAS unsigned*)(lds + (bufoff) + ldsw + _i * 8192), 16, 0, 0); } while (0)
; #define PG8_LDA(dst, b, h) do { _Pragma("unroll") for (int m = 0; m < 4; ++m) _Pragma("unroll") for (int k = 0; k < 2; ++k) dst[m][k] = *(const LAS bf16x8*)(lds + PG8_SA(b, h) + aoff + m * 2048 + k * 1024); } while (0)
; #define PG8_LDB(dst, b, h) do { _Pragma("unroll") for (int n = 0; n < 2; ++n) _Pragma("unroll") for (int k = 0; k < 2; ++k) dst[n][k] = *(const LAS bf16x8*)(lds + PG8_SB(b, h) + boff + n * 2048 + k * 1024); } while (0)
; #define PG8_MMA(ai, bj, At, Bt) do { __builtin_amdgcn_s_setprio(1); _Pragma("unroll") for (int m = 0; m < 4; ++m) _Pragma("unroll") for (int n = 0; n < 2; ++n) _Pragma("unroll") for (int k = 0; k < 2; ++k) \
;         acc[ai][bj][m][n] = __builtin_amdgcn_mfma_f32_16x16x32_bf16(Bt[n][k], At[m][k], acc[ai][bj][m][n], 0, 0, 0); __builtin_amdgcn_s_setprio(0); } while (0)
; #define PG8_WAIT_V(n) asm volatile("s_waitcnt vmcnt(" #n ")" ::: "memory")
; #define PG8_WAIT_L(n) asm volatile("s_waitcnt lgkmcnt(" #n ")" ::: "memory")
; #define PG8_BAR __builtin_amdgcn_s_barrier()
; #define PG8_SCHED __builtin_amdgcn_sched_barrier(0)
; template <class Epi>
; DI void gemm_phase(LAS unsigned char* lds, const Gemm g, const StaticOrder& S, const Epi& E, const int tid) {
;     ...
;             PG8_LDA(At, 0, 1); PG8_STAGE(PG8_SA(0, 0), a2, voffA);
;             PG8_BAR; PG8_WAIT_L(0); PG8_MMA(1, 0, At, B0); PG8_BAR; PG8_SCHED;
;             PG8_STAGE(PG8_SB(0, 1), b2 + hstepB, voffB);
;             PG8_WAIT_V(6); PG8_BAR; PG8_MMA(1, 1, At, B1); PG8_BAR;
;             PG8_LDB(B0, 1, 0); PG8_SCHED; PG8_LDA(At, 1, 0); PG8_STAGE(PG8_SA(0, 1), a2 + hstepA, voffA);
;             PG8_WAIT_L(8); PG8_BAR; PG8_WAIT_L(0); PG8_MMA(0, 0, At, B0); PG8_BAR; PG8_SCHED;
	ds_read_b128 v[162:165], v141 offset:16384
	ds_read_b128 v[166:169], v141 offset:17408
	ds_read_b128 v[178:181], v141 offset:18432
	ds_read_b128 v[182:185], v141 offset:19456
	ds_read_b128 v[186:189], v141 offset:20480
	ds_read_b128 v[190:193], v141 offset:21504
	ds_read_b128 v[194:197], v141 offset:22528
	ds_read_b128 v[198:201], v141 offset:23552
	global_load_lds_dwordx4 v130, s[8:9]
	s_mov_b32 m0, s46
	s_nop 0
	global_load_lds_dwordx4 v132, s[8:9]
	s_barrier
	s_waitcnt lgkmcnt(0)
	s_setprio 1
	s_waitcnt lgkmcnt(0)
	v_mfma_f32_16x16x32_bf16 v[62:65], v[142:145], v[162:165], v[62:65]
	v_mfma_f32_16x16x32_bf16 v[58:61], v[150:153], v[162:165], v[58:61]
	v_mfma_f32_16x16x32_bf16 v[54:57], v[142:145], v[178:181], v[54:57]
	v_mfma_f32_16x16x32_bf16 v[50:53], v[150:153], v[178:181], v[50:53]
	v_mfma_f32_16x16x32_bf16 v[38:41], v[142:145], v[186:189], v[38:41]
	v_mfma_f32_16x16x32_bf16 v[34:37], v[150:153], v[186:189], v[34:37]
	v_mfma_f32_16x16x32_bf16 v[22:25], v[142:145], v[194:197], v[22:25]
	v_mfma_f32_16x16x32_bf16 v[18:21], v[150:153], v[194:197], v[18:21]
	v_mfma_f32_16x16x32_bf16 v[62:65], v[146:149], v[166:169], v[62:65]
	v_mfma_f32_16x16x32_bf16 v[58:61], v[158:161], v[166:169], v[58:61]
	v_mfma_f32_16x16x32_bf16 v[54:57], v[146:149], v[182:185], v[54:57]
	v_mfma_f32_16x16x32_bf16 v[50:53], v[158:161], v[182:185], v[50:53]
	v_mfma_f32_16x16x32_bf16 v[38:41], v[146:149], v[190:193], v[38:41]
	v_mfma_f32_16x16x32_bf16 v[34:37], v[158:161], v[190:193], v[34:37]
	v_mfma_f32_16x16x32_bf16 v[22:25], v[146:149], v[198:201], v[22:25]
	v_mfma_f32_16x16x32_bf16 v[18:21], v[158:161], v[198:201], v[18:21]
	s_setprio 0
	s_barrier
	s_add_u32 s58, s6, 0x80000
	s_addc_u32 s59, s7, 0
	s_add_i32 s60, s61, s28
	s_mov_b32 m0, s60
	s_nop 0
	global_load_lds_dwordx4 v0, s[58:59]
	s_add_i32 m0, s60, 0x2000
	s_nop 0
	global_load_lds_dwordx4 v134, s[58:59]
	s_waitcnt vmcnt(6)
	s_barrier
	s_setprio 1
	v_mfma_f32_16x16x32_bf16 v[46:49], v[202:205], v[162:165], v[46:49]
	v_mfma_f32_16x16x32_bf16 v[42:45], v[210:213], v[162:165], v[42:45]
	v_mfma_f32_16x16x32_bf16 v[30:33], v[202:205], v[178:181], v[30:33]
	v_mfma_f32_16x16x32_bf16 v[26:29], v[210:213], v[178:181], v[26:29]
	v_mfma_f32_16x16x32_bf16 v[14:17], v[202:205], v[186:189], v[14:17]
	v_mfma_f32_16x16x32_bf16 v[10:13], v[210:213], v[186:189], v[10:13]
	v_mfma_f32_16x16x32_bf16 v[6:9], v[202:205], v[194:197], v[6:9]
	v_mfma_f32_16x16x32_bf16 v[2:5], v[210:213], v[194:197], v[2:5]
	v_mfma_f32_16x16x32_bf16 v[46:49], v[206:209], v[166:169], v[46:49]
	v_mfma_f32_16x16x32_bf16 v[42:45], v[214:217], v[166:169], v[42:45]
	v_mfma_f32_16x16x32_bf16 v[30:33], v[206:209], v[182:185], v[30:33]
	v_mfma_f32_16x16x32_bf16 v[26:29], v[214:217], v[182:185], v[26:29]
	v_mfma_f32_16x16x32_bf16 v[14:17], v[206:209], v[190:193], v[14:17]
	v_mfma_f32_16x16x32_bf16 v[10:13], v[214:217], v[190:193], v[10:13]
	v_mfma_f32_16x16x32_bf16 v[6:9], v[206:209], v[198:201], v[6:9]
	v_mfma_f32_16x16x32_bf16 v[2:5], v[214:217], v[198:201], v[2:5]
	s_setprio 0
	s_add_i32 s58, 0, 0x18000
	v_add_u32_e32 v158, s58, v139
	s_barrier
	ds_read_b128 v[142:145], v158
	ds_read_b128 v[146:149], v158 offset:1024
	ds_read_b128 v[150:153], v158 offset:2048
	ds_read_b128 v[158:161], v158 offset:3072
	s_add_u32 s8, s8, 0x10000
	s_addc_u32 s9, s9, 0
	s_mov_b32 m0, s47
	ds_read_b128 v[162:165], v141 offset:32768
	ds_read_b128 v[166:169], v141 offset:33792
	ds_read_b128 v[178:181], v141 offset:34816
	ds_read_b128 v[182:185], v141 offset:35840
	ds_read_b128 v[186:189], v141 offset:36864
	ds_read_b128 v[190:193], v141 offset:37888
	ds_read_b128 v[194:197], v141 offset:38912
	ds_read_b128 v[198:201], v141 offset:39936
	global_load_lds_dwordx4 v130, s[8:9]
	s_mov_b32 m0, s48
	s_nop 0
	global_load_lds_dwordx4 v132, s[8:9]
	s_waitcnt lgkmcnt(8)
	s_barrier
	s_waitcnt lgkmcnt(0)
	s_setprio 1
	s_waitcnt lgkmcnt(0)
	v_mfma_f32_16x16x32_bf16 v[126:129], v[142:145], v[162:165], v[126:129]
	v_mfma_f32_16x16x32_bf16 v[122:125], v[150:153], v[162:165], v[122:125]
	v_mfma_f32_16x16x32_bf16 v[118:121], v[142:145], v[178:181], v[118:121]
	v_mfma_f32_16x16x32_bf16 v[114:117], v[150:153], v[178:181], v[114:117]
	v_mfma_f32_16x16x32_bf16 v[102:105], v[142:145], v[186:189], v[102:105]
	v_mfma_f32_16x16x32_bf16 v[98:101], v[150:153], v[186:189], v[98:101]
	v_mfma_f32_16x16x32_bf16 v[86:89], v[142:145], v[194:197], v[86:89]
	v_mfma_f32_16x16x32_bf16 v[82:85], v[150:153], v[194:197], v[82:85]
	v_mfma_f32_16x16x32_bf16 v[126:129], v[146:149], v[166:169], v[126:129]
	v_mfma_f32_16x16x32_bf16 v[122:125], v[158:161], v[166:169], v[122:125]
	v_mfma_f32_16x16x32_bf16 v[118:121], v[146:149], v[182:185], v[118:121]
	v_mfma_f32_16x16x32_bf16 v[114:117], v[158:161], v[182:185], v[114:117]
	v_mfma_f32_16x16x32_bf16 v[102:105], v[146:149], v[190:193], v[102:105]
	v_mfma_f32_16x16x32_bf16 v[98:101], v[158:161], v[190:193], v[98:101]
	v_mfma_f32_16x16x32_bf16 v[86:89], v[146:149], v[198:201], v[86:89]
	v_mfma_f32_16x16x32_bf16 v[82:85], v[158:161], v[198:201], v[82:85]
	s_setprio 0
	s_barrier
; #define PG8_STAGE(bufoff, gbase, voff) do { _Pragma("unroll") for (int _i = 0; _i < 2; ++_i) \
;         __builtin_amdgcn_global_load_lds((const unsigned*)((const char*)(gbase) + (voff)[_i]), (LAS unsigned*)(lds + (bufoff) + ldsw + _i * 8192), 16, 0, 0); } while (0)
; #define PG8_LDA(dst, b, h) do { _Pragma("unroll") for (int m = 0; m < 4; ++m) _Pragma("unroll") for (int k = 0; k < 2; ++k) dst[m][k] = *(const LAS bf16x8*)(lds + PG8_SA(b, h) + aoff + m * 2048 + k * 1024); } while (0)
; #define PG8_LDB(dst, b, h) do { _Pragma("unroll") for (int n = 0; n < 2; ++n) _Pragma("unroll") for (int k = 0; k < 2; ++k) dst[n][k] = *(const LAS bf16x8*)(lds + PG8_SB(b, h) + boff + n * 2048 + k * 1024); } while (0)
; #define PG8_MMA(ai, bj, At, Bt) do { __builtin_amdgcn_s_setprio(1); _Pragma("unroll") for (int m = 0; m < 4; ++m) _Pragma("unroll") for (int n = 0; n < 2; ++n) _Pragma("unroll") for (int k = 0; k < 2; ++k) \
;         acc[ai][bj][m][n] = __builtin_amdgcn_mfma_f32_16x16x32_bf16(Bt[n][k], At[m][k], acc[ai][bj][m][n], 0, 0, 0); __builtin_amdgcn_s_setprio(0); } while (0)
; #define PG8_WAIT_V(n) asm volatile("s_waitcnt vmcnt(" #n ")" ::: "memory")
; #define PG8_WAIT_L(n) asm volatile("s_waitcnt lgkmcnt(" #n ")" ::: "memory")
; #define PG8_BAR __builtin_amdgcn_s_barrier()
; #define PG8_SCHED __builtin_amdgcn_sched_barrier(0)
; template <class Epi>
; DI void gemm_phase(LAS unsigned char* lds, const Gemm g, const StaticOrder& S, const Epi& E, const int tid) {
;     ...
;             PG8_WAIT_L(8); PG8_BAR; PG8_WAIT_L(0); PG8_MMA(0, 0, At, B0); PG8_BAR; PG8_SCHED;
;             PG8_LDB(B1, 1, 1); PG8_STAGE(PG8_SB(1, 0), b3, voffB);
;             PG8_BAR; PG8_WAIT_L(0); PG8_MMA(0, 1, At, B1); PG8_BAR;
;             PG8_LDA(At, 1, 1); PG8_STAGE(PG8_SA(1, 0), a3, voffA);
;             PG8_BAR; PG8_WAIT_L(0); PG8_MMA(1, 0, At, B0); PG8_BAR; PG8_SCHED;
;             PG8_STAGE(PG8_SB(1, 1), b3 + hstepB, voffB);
;             PG8_WAIT_V(6); PG8_BAR; PG8_MMA(1, 1, At, B1); PG8_BAR;
	s_add_i32 s8, 0, 0x1c000
	s_add_i32 s9, s58, s28
	v_add_u32_e32 v173, s8, v139
	s_add_u32 s58, s6, s84
	s_addc_u32 s59, s7, s85
	s_mov_b32 m0, s9
	ds_read_b128 v[202:205], v173
	ds_read_b128 v[206:209], v173 offset:1024
	ds_read_b128 v[210:213], v173 offset:2048
	ds_read_b128 v[214:217], v173 offset:3072
	global_load_lds_dwordx4 v0, s[58:59]
	s_add_i32 m0, s9, 0x2000
	s_nop 0
	global_load_lds_dwordx4 v134, s[58:59]
	s_barrier
	s_waitcnt lgkmcnt(0)
	s_setprio 1
	s_waitcnt lgkmcnt(0)
	v_mfma_f32_16x16x32_bf16 v[110:113], v[202:205], v[162:165], v[110:113]
	v_mfma_f32_16x16x32_bf16 v[106:109], v[210:213], v[162:165], v[106:109]
	v_mfma_f32_16x16x32_bf16 v[94:97], v[202:205], v[178:181], v[94:97]
	v_mfma_f32_16x16x32_bf16 v[90:93], v[210:213], v[178:181], v[90:93]
	v_mfma_f32_16x16x32_bf16 v[78:81], v[202:205], v[186:189], v[78:81]
	v_mfma_f32_16x16x32_bf16 v[74:77], v[210:213], v[186:189], v[74:77]
	v_mfma_f32_16x16x32_bf16 v[70:73], v[202:205], v[194:197], v[70:73]
	v_mfma_f32_16x16x32_bf16 v[66:69], v[210:213], v[194:197], v[66:69]
	v_mfma_f32_16x16x32_bf16 v[110:113], v[206:209], v[166:169], v[110:113]
	v_mfma_f32_16x16x32_bf16 v[106:109], v[214:217], v[166:169], v[106:109]
	v_mfma_f32_16x16x32_bf16 v[94:97], v[206:209], v[182:185], v[94:97]
	v_mfma_f32_16x16x32_bf16 v[90:93], v[214:217], v[182:185], v[90:93]
	v_mfma_f32_16x16x32_bf16 v[78:81], v[206:209], v[190:193], v[78:81]
	v_mfma_f32_16x16x32_bf16 v[74:77], v[214:217], v[190:193], v[74:77]
	v_mfma_f32_16x16x32_bf16 v[70:73], v[206:209], v[198:201], v[70:73]
	v_mfma_f32_16x16x32_bf16 v[66:69], v[214:217], v[198:201], v[66:69]
	s_setprio 0
	s_add_u32 s58, s4, s96
	s_addc_u32 s59, s5, s97
	s_mov_b32 m0, s49
	s_barrier
	ds_read_b128 v[162:165], v141 offset:49152
	ds_read_b128 v[166:169], v141 offset:50176
	ds_read_b128 v[178:181], v141 offset:51200
	ds_read_b128 v[182:185], v141 offset:52224
	ds_read_b128 v[186:189], v141 offset:53248
	ds_read_b128 v[190:193], v141 offset:54272
	ds_read_b128 v[194:197], v141 offset:55296
	ds_read_b128 v[198:201], v141 offset:56320
	global_load_lds_dwordx4 v130, s[58:59]
	s_mov_b32 m0, s50
	s_nop 0
	global_load_lds_dwordx4 v132, s[58:59]
	s_barrier
	s_waitcnt lgkmcnt(0)
	s_setprio 1
	s_waitcnt lgkmcnt(0)
	v_mfma_f32_16x16x32_bf16 v[62:65], v[142:145], v[162:165], v[62:65]
	v_mfma_f32_16x16x32_bf16 v[58:61], v[150:153], v[162:165], v[58:61]
	v_mfma_f32_16x16x32_bf16 v[54:57], v[142:145], v[178:181], v[54:57]
	v_mfma_f32_16x16x32_bf16 v[50:53], v[150:153], v[178:181], v[50:53]
	v_mfma_f32_16x16x32_bf16 v[38:41], v[142:145], v[186:189], v[38:41]
	v_mfma_f32_16x16x32_bf16 v[34:37], v[150:153], v[186:189], v[34:37]
	v_mfma_f32_16x16x32_bf16 v[22:25], v[142:145], v[194:197], v[22:25]
	v_mfma_f32_16x16x32_bf16 v[18:21], v[150:153], v[194:197], v[18:21]
	v_mfma_f32_16x16x32_bf16 v[62:65], v[146:149], v[166:169], v[62:65]
	v_mfma_f32_16x16x32_bf16 v[58:61], v[158:161], v[166:169], v[58:61]
	v_mfma_f32_16x16x32_bf16 v[54:57], v[146:149], v[182:185], v[54:57]
	v_mfma_f32_16x16x32_bf16 v[50:53], v[158:161], v[182:185], v[50:53]
	v_mfma_f32_16x16x32_bf16 v[38:41], v[146:149], v[190:193], v[38:41]
	v_mfma_f32_16x16x32_bf16 v[34:37], v[158:161], v[190:193], v[34:37]
	v_mfma_f32_16x16x32_bf16 v[22:25], v[146:149], v[198:201], v[22:25]
	v_mfma_f32_16x16x32_bf16 v[18:21], v[158:161], v[198:201], v[18:21]
	s_setprio 0
	s_barrier
	s_add_u32 s4, s6, 0x80080
	s_addc_u32 s5, s7, 0
	s_add_i32 s6, s8, s28
	s_mov_b32 m0, s6
	s_nop 0
	global_load_lds_dwordx4 v0, s[4:5]
	s_add_i32 m0, s6, 0x2000
	s_nop 0
	global_load_lds_dwordx4 v134, s[4:5]
	s_waitcnt vmcnt(6)
	s_barrier
	s_setprio 1
	v_mfma_f32_16x16x32_bf16 v[46:49], v[202:205], v[162:165], v[46:49]
	v_mfma_f32_16x16x32_bf16 v[42:45], v[210:213], v[162:165], v[42:45]
	v_mfma_f32_16x16x32_bf16 v[30:33], v[202:205], v[178:181], v[30:33]
	v_mfma_f32_16x16x32_bf16 v[26:29], v[210:213], v[178:181], v[26:29]
	v_mfma_f32_16x16x32_bf16 v[14:17], v[202:205], v[186:189], v[14:17]
	v_mfma_f32_16x16x32_bf16 v[10:13], v[210:213], v[186:189], v[10:13]
	v_mfma_f32_16x16x32_bf16 v[6:9], v[202:205], v[194:197], v[6:9]
	v_mfma_f32_16x16x32_bf16 v[2:5], v[210:213], v[194:197], v[2:5]
	v_mfma_f32_16x16x32_bf16 v[46:49], v[206:209], v[166:169], v[46:49]
	v_mfma_f32_16x16x32_bf16 v[42:45], v[214:217], v[166:169], v[42:45]
	v_mfma_f32_16x16x32_bf16 v[30:33], v[206:209], v[182:185], v[30:33]
	v_mfma_f32_16x16x32_bf16 v[26:29], v[214:217], v[182:185], v[26:29]
	v_mfma_f32_16x16x32_bf16 v[14:17], v[206:209], v[190:193], v[14:17]
	v_mfma_f32_16x16x32_bf16 v[10:13], v[214:217], v[190:193], v[10:13]
	v_mfma_f32_16x16x32_bf16 v[6:9], v[206:209], v[198:201], v[6:9]
	v_mfma_f32_16x16x32_bf16 v[2:5], v[214:217], v[198:201], v[2:5]
	s_setprio 0
	s_addk_i32 s41, 0x2000
	s_add_i32 s56, s56, 0x10000
	s_add_i32 s57, s57, 2
	s_add_u32 s38, s38, 0x100
	s_addc_u32 s39, s39, 0
	s_cmp_gt_u32 s57, 29
	s_barrier
	s_cbranch_scc1 .LBB0_276
